# wave sums in h1/mid/final: ds_bpermute butterflies replaced by DPP row ops + row_bcast + readlane (bitwise identical)
# speedup vs baseline: 1.0020x; 1.0020x over previous
; __device__ __forceinline__ v4u pack8(const float (&f)[8]) { v4u w; w.x = pk2(f[0], f[1]); w.y = pk2(f[2], f[3]); w.z = pk2(f[4], f[5]); w.w = pk2(f[6], f[7]); return w; }
; __device__ __forceinline__ void phase_h1(const Args& a, int lane, int wave) {
;     ...
;         for (int r = 0; r < 16; ++r) {
;             { const float* xr = a.in[I_X] + (size_t)(m0 + (r < 15 ? r + 1 : r)) * D + 8 * lane;
; #pragma unroll
;               for (int j = 0; j < 4; ++j) { vn[j][0] = *(const f32x4*)(xr + 512 * j); vn[j][1] = *(const f32x4*)(xr + 512 * j + 4); } }
;             float ss = 0.f;
; #pragma unroll
;             for (int j = 0; j < 4; ++j)
; #pragma unroll
;                 for (int q = 0; q < 2; ++q) ss += (v[j][q].x * v[j][q].x + v[j][q].y * v[j][q].y) + (v[j][q].z * v[j][q].z + v[j][q].w * v[j][q].w);
;             const float rstd = rsqrtf(wave_sum(ss) * (1.0f / D) + EPS);
;             bf16* hr = H + (size_t)(m0 + r) * D + 8 * lane;
; #pragma unroll
;             for (int j = 0; j < 4; ++j) { float o[8];
; #pragma unroll
;                 for (int e = 0; e < 8; ++e) o[e] = v[j][e >> 2][e & 3] * rstd * A[j][e] + B[j][e];
;                 *(v4u*)(hr + 512 * j) = pack8(o); }
.LBB0_147:
	v_lshl_add_u64 v[80:81], v[156:157], 0, s[22:23]
	s_waitcnt vmcnt(14)
	v_mov_b32_e32 v84, v37
	v_mov_b32_e32 v85, v33
	v_mov_b32_e32 v88, v39
	v_mov_b32_e32 v89, v35
	s_waitcnt vmcnt(12)
	v_pk_mul_f32 v[64:65], v[46:47], v[46:47]
	v_pk_mul_f32 v[90:91], v[44:45], v[44:45]
	s_waitcnt vmcnt(11)
	v_mul_f32_e32 v93, v54, v54
	v_mul_f32_e32 v95, v55, v55
	v_mul_f32_e32 v92, v41, v41
	v_mul_f32_e32 v94, v43, v43
	s_waitcnt vmcnt(10)
	v_pk_mul_f32 v[66:67], v[50:51], v[50:51]
	v_pk_mul_f32 v[168:169], v[48:49], v[48:49]
	v_add_co_u32_e32 v182, vcc, s38, v80
	v_mov_b32_e32 v82, v36
	v_mov_b32_e32 v83, v32
	v_mov_b32_e32 v86, v38
	v_mov_b32_e32 v87, v34
	global_load_dwordx4 v[68:71], v[80:81], off offset:16
	global_load_dwordx4 v[76:79], v[80:81], off
	v_pk_mov_b32 v[176:177], v[90:91], v[64:65] op_sel:[1,0]
	v_mov_b32_e32 v91, v65
	v_pk_mov_b32 v[178:179], v[168:169], v[66:67] op_sel:[1,0]
	v_mov_b32_e32 v169, v67
	global_load_dwordx4 v[64:67], v[80:81], off offset:2064
	global_load_dwordx4 v[72:75], v[80:81], off offset:2048
	v_pk_mul_f32 v[84:85], v[84:85], v[84:85]
	v_lshl_add_u64 v[180:181], v[80:81], 0, s[14:15]
	v_pk_mul_f32 v[88:89], v[88:89], v[88:89]
	v_addc_co_u32_e32 v183, vcc, 0, v81, vcc
	v_lshl_add_u64 v[80:81], v[80:81], 0, s[16:17]
	v_pk_fma_f32 v[184:185], v[40:41], v[40:41], v[92:93] op_sel_hi:[1,1,0]
	v_pk_fma_f32 v[186:187], v[42:43], v[42:43], v[94:95] op_sel_hi:[1,1,0]
	v_pk_fma_f32 v[188:189], v[82:83], v[82:83], v[84:85]
	v_pk_fma_f32 v[190:191], v[86:87], v[86:87], v[88:89]
	v_pk_add_f32 v[176:177], v[176:177], v[90:91]
	v_mov_b32_e32 v185, v93
	v_mov_b32_e32 v187, v95
	global_load_dwordx4 v[88:91], v[180:181], off offset:16
	global_load_dwordx4 v[92:95], v[182:183], off
	s_nop 0
	global_load_dwordx4 v[80:83], v[80:81], off offset:16
	s_nop 0
	global_load_dwordx4 v[84:87], v[182:183], off offset:2048
	s_waitcnt vmcnt(9)
	v_mul_f32_e32 v170, v61, v61
	v_mul_f32_e32 v172, v63, v63
	s_waitcnt vmcnt(8)
	v_mul_f32_e32 v194, v58, v58
	v_mul_f32_e32 v195, v59, v59
	v_pk_fma_f32 v[170:171], v[60:61], v[60:61], v[170:171] op_sel_hi:[1,1,0]
	v_pk_fma_f32 v[172:173], v[62:63], v[62:63], v[172:173] op_sel_hi:[1,1,0]
	v_mov_b32_e32 v171, v194
	v_mov_b32_e32 v173, v195
	v_pk_add_f32 v[180:181], v[188:189], v[190:191]
	v_mul_f32_e32 v117, v52, v52
	v_mul_f32_e32 v167, v53, v53
	v_pk_add_f32 v[176:177], v[176:177], v[176:177] op_sel:[0,1] op_sel_hi:[1,0]
	v_pk_add_f32 v[170:171], v[170:171], v[172:173]
	v_pk_add_f32 v[172:173], v[180:181], v[180:181] op_sel:[0,1] op_sel_hi:[1,0]
	v_mov_b32_e32 v177, v167
	v_mov_b32_e32 v173, v117
	v_pk_add_f32 v[182:183], v[184:185], v[186:187]
	v_pk_add_f32 v[172:173], v[172:173], v[176:177]
	v_pk_add_f32 v[168:169], v[178:179], v[168:169]
	v_pk_add_f32 v[172:173], v[172:173], v[182:183]
	v_mul_f32_e32 v192, v56, v56
	v_mul_f32_e32 v193, v57, v57
	v_pk_add_f32 v[168:169], v[168:169], v[168:169] op_sel:[0,1] op_sel_hi:[1,0]
	v_pk_add_f32 v[172:173], v[172:173], v[172:173] op_sel:[0,1] op_sel_hi:[1,0]
	v_mov_b32_e32 v169, v193
	v_mov_b32_e32 v173, v192
	v_pk_add_f32 v[168:169], v[172:173], v[168:169]
	s_ashr_i32 s25, s24, 31
	v_pk_add_f32 v[168:169], v[168:169], v[170:171]
	s_lshl_b64 s[42:43], s[24:25], 12
	v_add_f32_e32 v117, v168, v169
	s_add_i32 s24, s24, 1
	v_lshl_add_u64 v[178:179], v[98:99], 0, s[42:43]
	s_add_u32 s22, s22, 0x2000
	s_addc_u32 s23, s23, 0
	s_waitcnt lgkmcnt(0)
	s_nop 1
	v_add_f32_dpp v117, v117, v117 quad_perm:[1,0,3,2] row_mask:0xf bank_mask:0xf
	s_cmp_eq_u32 s22, 0x1e000
	s_waitcnt lgkmcnt(0)
	s_nop 1
	v_add_f32_dpp v117, v117, v117 quad_perm:[2,3,0,1] row_mask:0xf bank_mask:0xf
	s_waitcnt lgkmcnt(0)
	s_nop 1
	v_add_f32_dpp v117, v117, v117 row_half_mirror row_mask:0xf bank_mask:0xf
	s_waitcnt lgkmcnt(0)
	s_nop 1
	v_add_f32_dpp v117, v117, v117 row_mirror row_mask:0xf bank_mask:0xf
	s_waitcnt lgkmcnt(0)
	s_nop 1
	v_add_f32_dpp v117, v117, v117 row_bcast:15 row_mask:0xa bank_mask:0xf
	s_waitcnt lgkmcnt(0)
	s_nop 1
	v_add_f32_dpp v117, v117, v117 row_bcast:31 row_mask:0xc bank_mask:0xf
	s_nop 0
	v_readlane_b32 s99, v117, 63
	s_nop 1
	v_mov_b32_e32 v117, s99
	v_fmamk_f32 v117, v117, 0x3a000000, v166
	v_mul_f32_e32 v167, 0x4b800000, v117
	v_cmp_gt_f32_e32 vcc, s39, v117
	s_nop 1
	v_cndmask_b32_e32 v117, v117, v167, vcc
	v_rsq_f32_e32 v117, v117
	s_nop 0
	v_mul_f32_e32 v167, 0x45800000, v117
	v_cndmask_b32_e32 v168, v117, v167, vcc
	v_pk_mul_f32 v[36:37], v[36:37], v[168:169] op_sel_hi:[1,0]
	v_pk_mul_f32 v[38:39], v[38:39], v[168:169] op_sel_hi:[1,0]
	v_pk_mul_f32 v[32:33], v[32:33], v[168:169] op_sel_hi:[1,0]
	v_pk_mul_f32 v[34:35], v[34:35], v[168:169] op_sel_hi:[1,0]
	v_pk_mul_f32 v[44:45], v[44:45], v[168:169] op_sel_hi:[1,0]
	v_pk_mul_f32 v[46:47], v[46:47], v[168:169] op_sel_hi:[1,0]
	v_pk_mul_f32 v[40:41], v[40:41], v[168:169] op_sel_hi:[1,0]
	v_pk_mul_f32 v[42:43], v[42:43], v[168:169] op_sel_hi:[1,0]
	v_pk_mul_f32 v[52:53], v[52:53], v[168:169] op_sel_hi:[1,0]
	v_pk_mul_f32 v[54:55], v[54:55], v[168:169] op_sel_hi:[1,0]
	v_pk_mul_f32 v[48:49], v[48:49], v[168:169] op_sel_hi:[1,0]
	v_pk_mul_f32 v[50:51], v[50:51], v[168:169] op_sel_hi:[1,0]
	v_pk_mul_f32 v[60:61], v[60:61], v[168:169] op_sel_hi:[1,0]
	v_pk_mul_f32 v[62:63], v[62:63], v[168:169] op_sel_hi:[1,0]
	v_pk_mul_f32 v[56:57], v[56:57], v[168:169] op_sel_hi:[1,0]
	v_pk_mul_f32 v[58:59], v[58:59], v[168:169] op_sel_hi:[1,0]
	v_pk_fma_f32 v[36:37], v[154:155], v[36:37], v[28:29]
	v_pk_fma_f32 v[38:39], v[152:153], v[38:39], v[30:31]
	v_pk_fma_f32 v[168:169], v[150:151], v[32:33], v[24:25]
	v_pk_fma_f32 v[170:171], v[148:149], v[34:35], v[26:27]
	v_pk_fma_f32 v[44:45], v[146:147], v[44:45], v[20:21]
	v_pk_fma_f32 v[46:47], v[144:145], v[46:47], v[22:23]
	v_pk_fma_f32 v[40:41], v[142:143], v[40:41], v[16:17]
	v_pk_fma_f32 v[42:43], v[140:141], v[42:43], v[18:19]
	v_pk_fma_f32 v[52:53], v[138:139], v[52:53], v[12:13]
	v_pk_fma_f32 v[54:55], v[136:137], v[54:55], v[14:15]
	v_pk_fma_f32 v[48:49], v[134:135], v[48:49], v[8:9]
	v_pk_fma_f32 v[50:51], v[132:133], v[50:51], v[10:11]
	v_pk_fma_f32 v[60:61], v[128:129], v[60:61], v[4:5]
	v_pk_fma_f32 v[62:63], v[126:127], v[62:63], v[6:7]
	v_pk_fma_f32 v[56:57], v[130:131], v[56:57], v[0:1]
	v_pk_fma_f32 v[58:59], v[124:125], v[58:59], v[2:3]
	v_cvt_pk_bf16_f32 v32, v36, v37
	v_cvt_pk_bf16_f32 v33, v38, v39
	v_cvt_pk_bf16_f32 v34, v168, v169
	v_cvt_pk_bf16_f32 v35, v170, v171
	v_cvt_pk_bf16_f32 v36, v44, v45
	v_cvt_pk_bf16_f32 v37, v46, v47
	v_cvt_pk_bf16_f32 v38, v40, v41
	v_cvt_pk_bf16_f32 v39, v42, v43
	v_cvt_pk_bf16_f32 v40, v52, v53
	v_cvt_pk_bf16_f32 v41, v54, v55
	v_cvt_pk_bf16_f32 v42, v48, v49
	v_cvt_pk_bf16_f32 v43, v50, v51
	v_cvt_pk_bf16_f32 v44, v60, v61
	v_cvt_pk_bf16_f32 v45, v62, v63
	v_cvt_pk_bf16_f32 v46, v56, v57
	v_cvt_pk_bf16_f32 v47, v58, v59
	global_store_dwordx4 v[178:179], v[32:35], off
	global_store_dwordx4 v[178:179], v[36:39], off offset:1024
	global_store_dwordx4 v[178:179], v[40:43], off offset:2048
	global_store_dwordx4 v[178:179], v[44:47], off offset:3072
	s_waitcnt vmcnt(10)
; __device__ __forceinline__ void phase_h1(const Args& a, int lane, int wave) {
;     ...
; #pragma unroll
;             for (int j = 0; j < 4; ++j) { v[j][0] = vn[j][0]; v[j][1] = vn[j][1]; }
;         }
	v_mov_b64_e32 v[36:37], v[76:77]
	v_mov_b64_e32 v[32:33], v[68:69]
	s_waitcnt vmcnt(8)
	v_mov_b64_e32 v[44:45], v[72:73]
	v_mov_b64_e32 v[40:41], v[64:65]
	s_waitcnt vmcnt(7)
	v_mov_b64_e32 v[48:49], v[88:89]
	s_waitcnt vmcnt(5)
	v_mov_b64_e32 v[56:57], v[80:81]
	v_mov_b64_e32 v[52:53], v[92:93]
	s_waitcnt vmcnt(4)
	v_mov_b64_e32 v[60:61], v[84:85]
	v_mov_b64_e32 v[38:39], v[78:79]
	v_mov_b64_e32 v[34:35], v[70:71]
	v_mov_b64_e32 v[46:47], v[74:75]
	v_mov_b64_e32 v[42:43], v[66:67]
	v_mov_b64_e32 v[50:51], v[90:91]
	v_mov_b64_e32 v[58:59], v[82:83]
	v_mov_b64_e32 v[54:55], v[94:95]
	v_mov_b64_e32 v[62:63], v[86:87]
	s_cbranch_scc0 .LBB0_147
; __device__ __forceinline__ v4u pack8(const float (&f)[8]) { v4u w; w.x = pk2(f[0], f[1]); w.y = pk2(f[2], f[3]); w.z = pk2(f[4], f[5]); w.w = pk2(f[6], f[7]); return w; }
; __device__ __forceinline__ void phase_h1(const Args& a, int lane, int wave) {
;     ...
;             float ss = 0.f;
; #pragma unroll
;             for (int j = 0; j < 4; ++j)
; #pragma unroll
;                 for (int q = 0; q < 2; ++q) ss += (v[j][q].x * v[j][q].x + v[j][q].y * v[j][q].y) + (v[j][q].z * v[j][q].z + v[j][q].w * v[j][q].w);
;             const float rstd = rsqrtf(wave_sum(ss) * (1.0f / D) + EPS);
;             bf16* hr = H + (size_t)(m0 + r) * D + 8 * lane;
; #pragma unroll
;             for (int j = 0; j < 4; ++j) { float o[8];
; #pragma unroll
;                 for (int e = 0; e < 8; ++e) o[e] = v[j][e >> 2][e & 3] * rstd * A[j][e] + B[j][e];
;                 *(v4u*)(hr + 512 * j) = pack8(o); }
;     ...
;         { const int r16 = lane & 15, q4 = lane >> 4;
;           const bf16* hrow = H + (size_t)(m0 + r16) * D + 8 * q4; const bf16* wrow = (const bf16*)(a.ws + WS_WIN) + (size_t)(NIN + r16) * D + 8 * q4;
;           f32x4 acc0 = (f32x4){0.f, 0.f, 0.f, 0.f}, acc1 = acc0;
	v_mov_b32_e32 v34, v77
	v_mov_b32_e32 v35, v69
	v_mov_b32_e32 v32, v76
	v_mov_b32_e32 v33, v68
	v_pk_mul_f32 v[34:35], v[34:35], v[34:35]
	v_mov_b32_e32 v36, v79
	v_mov_b32_e32 v37, v71
	v_pk_fma_f32 v[32:33], v[32:33], v[32:33], v[34:35]
	v_mov_b32_e32 v34, v78
	v_mov_b32_e32 v35, v70
	v_pk_mul_f32 v[36:37], v[36:37], v[36:37]
	s_or_b32 s22, s20, 15
	v_pk_fma_f32 v[34:35], v[34:35], v[34:35], v[36:37]
	v_pk_mul_f32 v[36:37], v[72:73], v[72:73]
	v_pk_add_f32 v[32:33], v[32:33], v[34:35]
	v_pk_mul_f32 v[34:35], v[74:75], v[74:75]
	v_pk_add_f32 v[32:33], v[32:33], v[32:33] op_sel:[0,1] op_sel_hi:[1,0]
	v_pk_mov_b32 v[38:39], v[36:37], v[34:35] op_sel:[1,0]
	v_mov_b32_e32 v37, v35
	v_pk_add_f32 v[34:35], v[38:39], v[36:37]
	v_mul_f32_e32 v36, v92, v92
	v_mul_f32_e32 v37, v93, v93
	v_pk_add_f32 v[34:35], v[34:35], v[34:35] op_sel:[0,1] op_sel_hi:[1,0]
	v_mov_b32_e32 v33, v36
	v_mov_b32_e32 v35, v37
	v_pk_add_f32 v[32:33], v[32:33], v[34:35]
	v_mul_f32_e32 v34, v65, v65
	v_mul_f32_e32 v36, v67, v67
	v_mul_f32_e32 v38, v94, v94
	v_mul_f32_e32 v39, v95, v95
	v_pk_fma_f32 v[34:35], v[64:65], v[64:65], v[34:35] op_sel_hi:[1,1,0]
	v_pk_fma_f32 v[36:37], v[66:67], v[66:67], v[36:37] op_sel_hi:[1,1,0]
	v_mov_b32_e32 v35, v38
	v_mov_b32_e32 v37, v39
	v_pk_add_f32 v[34:35], v[34:35], v[36:37]
	v_pk_mul_f32 v[36:37], v[88:89], v[88:89]
	v_pk_add_f32 v[32:33], v[32:33], v[34:35]
	v_pk_mul_f32 v[34:35], v[90:91], v[90:91]
	v_pk_add_f32 v[32:33], v[32:33], v[32:33] op_sel:[0,1] op_sel_hi:[1,0]
	v_pk_mov_b32 v[38:39], v[36:37], v[34:35] op_sel:[1,0]
	v_mov_b32_e32 v37, v35
	v_pk_add_f32 v[34:35], v[38:39], v[36:37]
	v_mul_f32_e32 v36, v80, v80
	v_mul_f32_e32 v37, v81, v81
	v_pk_add_f32 v[34:35], v[34:35], v[34:35] op_sel:[0,1] op_sel_hi:[1,0]
	v_mov_b32_e32 v33, v36
	v_mov_b32_e32 v35, v37
	v_pk_add_f32 v[32:33], v[32:33], v[34:35]
	v_mul_f32_e32 v34, v85, v85
	v_mul_f32_e32 v36, v87, v87
	v_mul_f32_e32 v38, v82, v82
	v_mul_f32_e32 v39, v83, v83
	v_pk_fma_f32 v[34:35], v[84:85], v[84:85], v[34:35] op_sel_hi:[1,1,0]
	v_pk_fma_f32 v[36:37], v[86:87], v[86:87], v[36:37] op_sel_hi:[1,1,0]
	v_mov_b32_e32 v35, v38
	v_mov_b32_e32 v37, v39
	v_pk_add_f32 v[34:35], v[34:35], v[36:37]
	s_ashr_i32 s23, s22, 31
	v_pk_add_f32 v[32:33], v[32:33], v[34:35]
	s_lshl_b64 s[22:23], s[22:23], 12
	v_add_f32_e32 v32, v32, v33
	v_lshl_add_u64 v[36:37], v[98:99], 0, s[22:23]
	v_ashrrev_i32_e32 v117, 31, v116
	s_mov_b32 s9, 8
	s_waitcnt lgkmcnt(0)
	s_nop 1
	v_add_f32_dpp v32, v32, v32 quad_perm:[1,0,3,2] row_mask:0xf bank_mask:0xf
	s_waitcnt lgkmcnt(0)
	s_nop 1
	v_add_f32_dpp v32, v32, v32 quad_perm:[2,3,0,1] row_mask:0xf bank_mask:0xf
	s_waitcnt lgkmcnt(0)
	s_nop 1
	v_add_f32_dpp v32, v32, v32 row_half_mirror row_mask:0xf bank_mask:0xf
	s_waitcnt lgkmcnt(0)
	s_nop 1
	v_add_f32_dpp v32, v32, v32 row_mirror row_mask:0xf bank_mask:0xf
	s_waitcnt lgkmcnt(0)
	s_nop 1
	v_add_f32_dpp v32, v32, v32 row_bcast:15 row_mask:0xa bank_mask:0xf
	s_waitcnt lgkmcnt(0)
	s_nop 1
	v_add_f32_dpp v32, v32, v32 row_bcast:31 row_mask:0xc bank_mask:0xf
	s_nop 0
	v_readlane_b32 s99, v32, 63
	s_nop 1
	v_mov_b32_e32 v32, s99
	v_fmamk_f32 v32, v32, 0x3a000000, v166
	v_mul_f32_e32 v33, 0x4b800000, v32
	v_cmp_gt_f32_e32 vcc, s39, v32
	s_nop 1
	v_cndmask_b32_e32 v32, v32, v33, vcc
	v_rsq_f32_e32 v34, v32
	v_lshlrev_b64 v[32:33], 12, v[116:117]
	v_lshl_add_u64 v[32:33], s[80:81], 0, v[32:33]
	v_mul_f32_e32 v35, 0x45800000, v34
	v_cndmask_b32_e32 v34, v34, v35, vcc
	v_pk_mul_f32 v[38:39], v[76:77], v[34:35] op_sel_hi:[1,0]
	s_nop 0
	v_pk_fma_f32 v[28:29], v[154:155], v[38:39], v[28:29]
	v_pk_mul_f32 v[38:39], v[78:79], v[34:35] op_sel_hi:[1,0]
	s_nop 0
	v_pk_fma_f32 v[30:31], v[152:153], v[38:39], v[30:31]
	v_pk_mul_f32 v[38:39], v[68:69], v[34:35] op_sel_hi:[1,0]
	s_nop 0
	v_pk_fma_f32 v[38:39], v[150:151], v[38:39], v[24:25]
	v_pk_mul_f32 v[24:25], v[70:71], v[34:35] op_sel_hi:[1,0]
	s_nop 0
	v_pk_fma_f32 v[40:41], v[148:149], v[24:25], v[26:27]
	v_cvt_pk_bf16_f32 v24, v28, v29
	v_cvt_pk_bf16_f32 v25, v30, v31
	v_cvt_pk_bf16_f32 v26, v38, v39
	v_cvt_pk_bf16_f32 v27, v40, v41
	global_store_dwordx4 v[36:37], v[24:27], off
	s_nop 1
	v_pk_mul_f32 v[24:25], v[72:73], v[34:35] op_sel_hi:[1,0]
	s_nop 0
	v_pk_fma_f32 v[20:21], v[146:147], v[24:25], v[20:21]
	v_pk_mul_f32 v[24:25], v[74:75], v[34:35] op_sel_hi:[1,0]
	s_nop 0
	v_pk_fma_f32 v[22:23], v[144:145], v[24:25], v[22:23]
	v_pk_mul_f32 v[24:25], v[64:65], v[34:35] op_sel_hi:[1,0]
	s_nop 0
	v_pk_fma_f32 v[24:25], v[142:143], v[24:25], v[16:17]
	v_pk_mul_f32 v[16:17], v[66:67], v[34:35] op_sel_hi:[1,0]
	s_nop 0
	v_pk_fma_f32 v[26:27], v[140:141], v[16:17], v[18:19]
	v_cvt_pk_bf16_f32 v16, v20, v21
	v_cvt_pk_bf16_f32 v17, v22, v23
	v_cvt_pk_bf16_f32 v18, v24, v25
	v_cvt_pk_bf16_f32 v19, v26, v27
	global_store_dwordx4 v[36:37], v[16:19], off offset:1024
	s_nop 1
	v_pk_mul_f32 v[16:17], v[92:93], v[34:35] op_sel_hi:[1,0]
	s_nop 0
	v_pk_fma_f32 v[12:13], v[138:139], v[16:17], v[12:13]
	v_pk_mul_f32 v[16:17], v[94:95], v[34:35] op_sel_hi:[1,0]
	s_nop 0
	v_pk_fma_f32 v[14:15], v[136:137], v[16:17], v[14:15]
	v_pk_mul_f32 v[16:17], v[88:89], v[34:35] op_sel_hi:[1,0]
	s_nop 0
	v_pk_fma_f32 v[16:17], v[134:135], v[16:17], v[8:9]
	v_pk_mul_f32 v[8:9], v[90:91], v[34:35] op_sel_hi:[1,0]
	s_nop 0
	v_pk_fma_f32 v[18:19], v[132:133], v[8:9], v[10:11]
	v_cvt_pk_bf16_f32 v8, v12, v13
	v_cvt_pk_bf16_f32 v9, v14, v15
	v_cvt_pk_bf16_f32 v10, v16, v17
	v_cvt_pk_bf16_f32 v11, v18, v19
	global_store_dwordx4 v[36:37], v[8:11], off offset:2048
	v_mov_b64_e32 v[14:15], v[112:113]
	s_nop 0
	v_pk_mul_f32 v[8:9], v[84:85], v[34:35] op_sel_hi:[1,0]
	s_nop 0
	v_pk_fma_f32 v[4:5], v[128:129], v[8:9], v[4:5]
	v_pk_mul_f32 v[8:9], v[86:87], v[34:35] op_sel_hi:[1,0]
	s_nop 0
	v_pk_fma_f32 v[6:7], v[126:127], v[8:9], v[6:7]
	v_pk_mul_f32 v[8:9], v[80:81], v[34:35] op_sel_hi:[1,0]
	s_nop 0
	v_pk_fma_f32 v[8:9], v[130:131], v[8:9], v[0:1]
	v_pk_mul_f32 v[0:1], v[82:83], v[34:35] op_sel_hi:[1,0]
	s_nop 0
	v_pk_fma_f32 v[10:11], v[124:125], v[0:1], v[2:3]
	v_cvt_pk_bf16_f32 v0, v4, v5
	v_cvt_pk_bf16_f32 v1, v6, v7
	v_cvt_pk_bf16_f32 v2, v8, v9
	v_cvt_pk_bf16_f32 v3, v10, v11
	global_store_dwordx4 v[36:37], v[0:3], off offset:3072
	s_waitcnt vmcnt(0)
	v_mov_b64_e32 v[10:11], v[110:111]
	s_nop 0
	v_or_b32_e32 v0, s20, v158
	v_ashrrev_i32_e32 v1, 31, v0
	v_lshlrev_b64 v[0:1], 12, v[0:1]
	v_lshl_add_u64 v[8:9], v[100:101], 0, v[0:1]
	v_mov_b32_e32 v0, 0
	v_mov_b64_e32 v[12:13], v[8:9]
	v_mov_b32_e32 v1, v0
	v_mov_b32_e32 v2, v0
	v_mov_b32_e32 v3, v0
	v_mov_b32_e32 v4, v0
	v_mov_b32_e32 v5, v0
	v_mov_b32_e32 v6, v0
	v_mov_b32_e32 v7, v0

; __device__ __forceinline__ void phase_mid(const Args& a, int lane, int wave) {
;     ...
;             for (int j = 0; j < 4; ++j) { const f32x4 xa = *(const f32x4*)(a.in[I_X] + ro + 512 * j), xb = *(const f32x4*)(a.in[I_X] + ro + 512 * j + 4);
; #pragma unroll
;                 for (int e = 0; e < 8; ++e) { const float xv = (e < 4 ? xa[e & 3] : xb[e & 3]) + G[j][e] * (y[j][e] * rstd); y[j][e] = xv; s2 += xv * xv; }
;                 }
;             const float rstd2 = rsqrtf(wave_sum(s2) * (1.0f / D) + EPS);
.LBB0_603:
	s_or_b64 exec, exec, s[6:7]
	v_lshl_add_u64 v[172:173], v[56:57], 0, s[28:29]
	global_load_dwordx4 v[164:167], v[172:173], off offset:16
	global_load_dwordx4 v[168:171], v[172:173], off
	global_load_dwordx4 v[178:181], v[172:173], off offset:2064
	global_load_dwordx4 v[182:185], v[172:173], off offset:2048
	v_add_co_u32_e32 v198, vcc, s47, v172
	v_lshl_add_u64 v[186:187], v[172:173], 0, s[24:25]
	s_nop 0
	v_addc_co_u32_e32 v199, vcc, 0, v173, vcc
	global_load_dwordx4 v[186:189], v[186:187], off offset:16
	v_lshl_add_u64 v[172:173], v[172:173], 0, s[26:27]
	global_load_dwordx4 v[190:193], v[198:199], off
	global_load_dwordx4 v[194:197], v[172:173], off offset:16
	s_nop 0
	global_load_dwordx4 v[198:201], v[198:199], off offset:2048
	v_pk_mul_f32 v[124:125], v[156:157], v[124:125] op_sel_hi:[0,1]
	v_pk_mul_f32 v[126:127], v[156:157], v[126:127] op_sel_hi:[0,1]
	v_pk_mul_f32 v[128:129], v[156:157], v[128:129] op_sel_hi:[0,1]
	v_pk_mul_f32 v[130:131], v[156:157], v[130:131] op_sel_hi:[0,1]
	v_pk_mul_f32 v[132:133], v[156:157], v[132:133] op_sel_hi:[0,1]
	v_pk_mul_f32 v[134:135], v[156:157], v[134:135] op_sel_hi:[0,1]
	v_pk_mul_f32 v[136:137], v[156:157], v[136:137] op_sel_hi:[0,1]
	v_pk_mul_f32 v[138:139], v[156:157], v[138:139] op_sel_hi:[0,1]
	v_pk_mul_f32 v[140:141], v[156:157], v[140:141] op_sel_hi:[0,1]
	v_pk_mul_f32 v[142:143], v[156:157], v[142:143] op_sel_hi:[0,1]
	v_pk_mul_f32 v[144:145], v[156:157], v[144:145] op_sel_hi:[0,1]
	v_pk_mul_f32 v[146:147], v[156:157], v[146:147] op_sel_hi:[0,1]
	v_pk_mul_f32 v[148:149], v[156:157], v[148:149] op_sel_hi:[0,1]
	v_pk_mul_f32 v[150:151], v[156:157], v[150:151] op_sel_hi:[0,1]
	v_pk_mul_f32 v[152:153], v[156:157], v[152:153] op_sel_hi:[0,1]
	v_pk_mul_f32 v[154:155], v[156:157], v[154:155] op_sel_hi:[0,1]
	s_add_u32 s28, s28, 0x2000
	s_addc_u32 s29, s29, 0
	s_add_u32 s49, s49, 4
	s_addc_u32 s50, s50, 0
	s_cmp_eq_u32 s28, 0x20000
	v_lshl_add_u64 v[54:55], v[54:55], 0, s[24:25]
	s_waitcnt vmcnt(7)
	v_pk_fma_f32 v[128:129], v[66:67], v[128:129], v[164:165]
	s_waitcnt vmcnt(6)
	v_pk_fma_f32 v[124:125], v[58:59], v[124:125], v[168:169]
	v_pk_fma_f32 v[126:127], v[62:63], v[126:127], v[170:171]
	v_pk_mul_f32 v[170:171], v[124:125], v[124:125]
	v_pk_mul_f32 v[168:169], v[126:127], v[126:127]
	v_add_f32_e32 v156, v170, v171
	v_add_f32_e32 v156, v168, v156
	v_pk_fma_f32 v[130:131], v[70:71], v[130:131], v[166:167]
	v_pk_mul_f32 v[166:167], v[128:129], v[128:129]
	v_add_f32_e32 v156, v169, v156
	v_add_f32_e32 v156, v166, v156
	v_pk_mul_f32 v[164:165], v[130:131], v[130:131]
	v_add_f32_e32 v156, v167, v156
	s_waitcnt vmcnt(4)
	v_pk_fma_f32 v[132:133], v[74:75], v[132:133], v[182:183]
	v_add_f32_e32 v156, v164, v156
	v_pk_mul_f32 v[182:183], v[132:133], v[132:133]
	v_add_f32_e32 v156, v165, v156
	v_pk_fma_f32 v[134:135], v[78:79], v[134:135], v[184:185]
	v_add_f32_e32 v156, v182, v156
	v_pk_fma_f32 v[138:139], v[86:87], v[138:139], v[180:181]
	v_pk_mul_f32 v[180:181], v[134:135], v[134:135]
	v_add_f32_e32 v156, v183, v156
	v_pk_fma_f32 v[136:137], v[82:83], v[136:137], v[178:179]
	v_add_f32_e32 v156, v180, v156
	v_pk_mul_f32 v[178:179], v[136:137], v[136:137]
	v_add_f32_e32 v156, v181, v156
	v_add_f32_e32 v156, v178, v156
	v_pk_mul_f32 v[172:173], v[138:139], v[138:139]
	v_add_f32_e32 v156, v179, v156
	s_waitcnt vmcnt(2)
	v_pk_fma_f32 v[140:141], v[90:91], v[140:141], v[190:191]
	v_add_f32_e32 v156, v172, v156
	v_pk_fma_f32 v[146:147], v[102:103], v[146:147], v[188:189]
	v_pk_mul_f32 v[188:189], v[140:141], v[140:141]
	v_add_f32_e32 v156, v173, v156
	v_pk_fma_f32 v[142:143], v[94:95], v[142:143], v[192:193]
	v_add_f32_e32 v156, v188, v156
	v_pk_fma_f32 v[144:145], v[98:99], v[144:145], v[186:187]
	v_pk_mul_f32 v[186:187], v[142:143], v[142:143]
	v_add_f32_e32 v156, v189, v156
	v_add_f32_e32 v156, v186, v156
	v_pk_mul_f32 v[184:185], v[144:145], v[144:145]
	v_add_f32_e32 v156, v187, v156
	v_add_f32_e32 v156, v184, v156
	v_pk_mul_f32 v[170:171], v[146:147], v[146:147]
	v_add_f32_e32 v156, v185, v156
	s_waitcnt vmcnt(0)
	v_pk_fma_f32 v[148:149], v[106:107], v[148:149], v[198:199]
	v_add_f32_e32 v156, v170, v156
	v_pk_fma_f32 v[154:155], v[118:119], v[154:155], v[196:197]
	v_pk_mul_f32 v[196:197], v[148:149], v[148:149]
	v_add_f32_e32 v156, v171, v156
	v_pk_fma_f32 v[150:151], v[110:111], v[150:151], v[200:201]
	v_add_f32_e32 v156, v196, v156
	v_pk_fma_f32 v[152:153], v[114:115], v[152:153], v[194:195]
	v_pk_mul_f32 v[194:195], v[150:151], v[150:151]
	v_add_f32_e32 v156, v197, v156
	v_add_f32_e32 v156, v194, v156
	v_pk_mul_f32 v[192:193], v[152:153], v[152:153]
	v_add_f32_e32 v156, v195, v156
	v_add_f32_e32 v156, v192, v156
	v_pk_mul_f32 v[190:191], v[154:155], v[154:155]
	v_add_f32_e32 v156, v193, v156
	v_add_f32_e32 v156, v190, v156
	v_add_f32_e32 v156, v191, v156
	v_add_co_u32_e64 v164, s[6:7], s48, v122
	s_waitcnt lgkmcnt(0)
	s_nop 1
	v_add_f32_dpp v156, v156, v156 quad_perm:[1,0,3,2] row_mask:0xf bank_mask:0xf
	v_addc_co_u32_e64 v165, s[6:7], 0, v123, s[6:7]
	s_waitcnt lgkmcnt(0)
	s_nop 1
	v_add_f32_dpp v156, v156, v156 quad_perm:[2,3,0,1] row_mask:0xf bank_mask:0xf
	s_waitcnt lgkmcnt(0)
	s_nop 1
	v_add_f32_dpp v156, v156, v156 row_half_mirror row_mask:0xf bank_mask:0xf
	s_waitcnt lgkmcnt(0)
	s_nop 1
	v_add_f32_dpp v156, v156, v156 row_mirror row_mask:0xf bank_mask:0xf
	s_waitcnt lgkmcnt(0)
	s_nop 1
	v_add_f32_dpp v156, v156, v156 row_bcast:15 row_mask:0xa bank_mask:0xf
	s_waitcnt lgkmcnt(0)
; __device__ __forceinline__ v4u pack8(const float (&f)[8]) { v4u w; w.x = pk2(f[0], f[1]); w.y = pk2(f[2], f[3]); w.z = pk2(f[4], f[5]); w.w = pk2(f[6], f[7]); return w; }
; __device__ __forceinline__ void phase_mid(const Args& a, int lane, int wave) {
;     ...
;             const float rstd2 = rsqrtf(wave_sum(s2) * (1.0f / D) + EPS);
; #pragma unroll
;             for (int j = 0; j < 4; ++j) { float o[8];
; #pragma unroll
;                 for (int e = 0; e < 8; ++e) o[e] = y[j][e] * rstd2 * A[j][e] + B[j][e];
;                 *(v4u*)(H + ro + 512 * j) = pack8(o); }
	s_nop 1
	v_add_f32_dpp v156, v156, v156 row_bcast:31 row_mask:0xc bank_mask:0xf
	s_nop 0
	v_readlane_b32 s99, v156, 63
	s_nop 1
	v_mov_b32_e32 v156, s99
	v_fmamk_f32 v156, v156, 0x3a000000, v162
	v_mul_f32_e32 v163, 0x4b800000, v156
	v_cmp_gt_f32_e32 vcc, s46, v156
	s_nop 1
	v_cndmask_b32_e32 v156, v156, v163, vcc
	v_rsq_f32_e32 v156, v156
	s_nop 0
	v_mul_f32_e32 v122, 0x45800000, v156
	v_cndmask_b32_e32 v156, v156, v122, vcc
	v_pk_mul_f32 v[122:123], v[124:125], v[156:157] op_sel_hi:[1,0]
	v_pk_mul_f32 v[124:125], v[126:127], v[156:157] op_sel_hi:[1,0]
	v_pk_mul_f32 v[126:127], v[128:129], v[156:157] op_sel_hi:[1,0]
	v_pk_mul_f32 v[128:129], v[130:131], v[156:157] op_sel_hi:[1,0]
	v_pk_mul_f32 v[130:131], v[132:133], v[156:157] op_sel_hi:[1,0]
	v_pk_mul_f32 v[132:133], v[134:135], v[156:157] op_sel_hi:[1,0]
	v_pk_mul_f32 v[134:135], v[136:137], v[156:157] op_sel_hi:[1,0]
	v_pk_mul_f32 v[136:137], v[138:139], v[156:157] op_sel_hi:[1,0]
	v_pk_mul_f32 v[138:139], v[140:141], v[156:157] op_sel_hi:[1,0]
	v_pk_mul_f32 v[140:141], v[142:143], v[156:157] op_sel_hi:[1,0]
	v_pk_mul_f32 v[142:143], v[144:145], v[156:157] op_sel_hi:[1,0]
	v_pk_mul_f32 v[144:145], v[146:147], v[156:157] op_sel_hi:[1,0]
	v_pk_fma_f32 v[122:123], v[60:61], v[122:123], v[4:5]
	v_pk_fma_f32 v[124:125], v[64:65], v[124:125], v[6:7]
	v_pk_fma_f32 v[126:127], v[68:69], v[126:127], v[0:1]
	v_pk_fma_f32 v[128:129], v[72:73], v[128:129], v[2:3]
	v_pk_fma_f32 v[130:131], v[76:77], v[130:131], v[8:9]
	v_pk_fma_f32 v[132:133], v[80:81], v[132:133], v[10:11]
	v_pk_fma_f32 v[134:135], v[84:85], v[134:135], v[12:13]
	v_pk_fma_f32 v[136:137], v[88:89], v[136:137], v[14:15]
	v_pk_fma_f32 v[138:139], v[92:93], v[138:139], v[16:17]
	v_pk_fma_f32 v[140:141], v[96:97], v[140:141], v[18:19]
	v_pk_fma_f32 v[142:143], v[100:101], v[142:143], v[20:21]
	v_pk_fma_f32 v[144:145], v[104:105], v[144:145], v[22:23]
	v_cvt_pk_bf16_f32 v122, v122, v123
	v_cvt_pk_bf16_f32 v123, v124, v125
	v_cvt_pk_bf16_f32 v124, v126, v127
	v_cvt_pk_bf16_f32 v125, v128, v129
	v_pk_mul_f32 v[146:147], v[148:149], v[156:157] op_sel_hi:[1,0]
	v_pk_mul_f32 v[148:149], v[150:151], v[156:157] op_sel_hi:[1,0]
	v_pk_mul_f32 v[150:151], v[152:153], v[156:157] op_sel_hi:[1,0]
	v_cvt_pk_bf16_f32 v126, v130, v131
	v_cvt_pk_bf16_f32 v127, v132, v133
	v_cvt_pk_bf16_f32 v128, v134, v135
	v_cvt_pk_bf16_f32 v129, v136, v137
	v_cvt_pk_bf16_f32 v130, v138, v139
	v_cvt_pk_bf16_f32 v131, v140, v141
	v_cvt_pk_bf16_f32 v132, v142, v143
	v_cvt_pk_bf16_f32 v133, v144, v145
	global_store_dwordx4 v[164:165], v[122:125], off
	global_store_dwordx4 v[164:165], v[126:129], off offset:1024
	global_store_dwordx4 v[164:165], v[130:133], off offset:2048
	v_pk_mul_f32 v[122:123], v[154:155], v[156:157] op_sel_hi:[1,0]
	v_pk_fma_f32 v[146:147], v[108:109], v[146:147], v[24:25]
	v_pk_fma_f32 v[148:149], v[112:113], v[148:149], v[26:27]
	v_pk_fma_f32 v[150:151], v[116:117], v[150:151], v[28:29]
	v_pk_fma_f32 v[126:127], v[120:121], v[122:123], v[30:31]
	v_cvt_pk_bf16_f32 v122, v146, v147
	v_cvt_pk_bf16_f32 v123, v148, v149
	v_cvt_pk_bf16_f32 v124, v150, v151
	v_cvt_pk_bf16_f32 v125, v126, v127
	global_store_dwordx4 v[164:165], v[122:125], off offset:3072
	s_cbranch_scc1 .LBB0_601
; __device__ __forceinline__ float wave_sum(float v) {
; #pragma unroll
;     for (int o = 1; o < 64; o <<= 1) v += __shfl_xor(v, o);
;     return v;
; }
; __device__ __forceinline__ void phase_mid(const Args& a, int lane, int wave) {
;     ...
;         for (int r = 0; r < 16; ++r) {
;             const size_t ro = (size_t)(m0 + r) * D + 8 * lane;
;             float y[4][8]; float ss = 0.f;
; #pragma unroll
;             for (int j = 0; j < 4; ++j) { unpack8(*(const v4u*)(Yb + ro + 512 * j), y[j]);
; #pragma unroll
;                 for (int e = 0; e < 8; ++e) ss += y[j][e] * y[j][e]; }
;             const float rstd = rsqrtf(wave_sum(ss) * (1.0f / D) + EPS);
;             if (lane == 0) ((float*)(a.ws + WS_RSTD))[m0 + r] = rstd;
.LBB0_604:
	s_nop 0
	v_lshl_add_u64 v[122:123], s[80:81], 0, v[54:55]
	v_add_co_u32_e32 v124, vcc, 0x16800000, v122
	s_nop 1
	v_addc_co_u32_e32 v125, vcc, 0, v123, vcc
	global_load_dwordx4 v[128:131], v[124:125], off
	global_load_dwordx4 v[136:139], v[124:125], off offset:1024
	global_load_dwordx4 v[144:147], v[124:125], off offset:2048
	global_load_dwordx4 v[152:155], v[124:125], off offset:3072
	s_waitcnt vmcnt(3)
	v_lshlrev_b32_e32 v124, 16, v128
	v_and_b32_e32 v125, 0xffff0000, v128
	v_lshlrev_b32_e32 v126, 16, v129
	v_and_b32_e32 v127, 0xffff0000, v129
	v_pk_mul_f32 v[164:165], v[124:125], v[124:125]
	v_pk_mul_f32 v[166:167], v[126:127], v[126:127]
	v_add_f32_e32 v156, v164, v165
	v_lshlrev_b32_e32 v128, 16, v130
	v_and_b32_e32 v129, 0xffff0000, v130
	v_add_f32_e32 v156, v166, v156
	v_pk_mul_f32 v[168:169], v[128:129], v[128:129]
	v_add_f32_e32 v156, v167, v156
	v_lshlrev_b32_e32 v130, 16, v131
	v_and_b32_e32 v131, 0xffff0000, v131
	v_add_f32_e32 v156, v168, v156
	v_pk_mul_f32 v[170:171], v[130:131], v[130:131]
	v_add_f32_e32 v156, v169, v156
	s_waitcnt vmcnt(2)
	v_lshlrev_b32_e32 v132, 16, v136
	v_and_b32_e32 v133, 0xffff0000, v136
	v_add_f32_e32 v156, v170, v156
	v_pk_mul_f32 v[172:173], v[132:133], v[132:133]
	v_add_f32_e32 v156, v171, v156
	v_lshlrev_b32_e32 v134, 16, v137
	v_and_b32_e32 v135, 0xffff0000, v137
	v_add_f32_e32 v156, v172, v156
	v_pk_mul_f32 v[178:179], v[134:135], v[134:135]
	v_add_f32_e32 v156, v173, v156
	v_lshlrev_b32_e32 v136, 16, v138
	v_and_b32_e32 v137, 0xffff0000, v138
	v_add_f32_e32 v156, v178, v156
	v_pk_mul_f32 v[180:181], v[136:137], v[136:137]
	v_add_f32_e32 v156, v179, v156
	v_lshlrev_b32_e32 v138, 16, v139
	v_and_b32_e32 v139, 0xffff0000, v139
	v_add_f32_e32 v156, v180, v156
	v_pk_mul_f32 v[182:183], v[138:139], v[138:139]
	v_add_f32_e32 v156, v181, v156
	s_waitcnt vmcnt(1)
	v_lshlrev_b32_e32 v140, 16, v144
	v_and_b32_e32 v141, 0xffff0000, v144
	v_add_f32_e32 v156, v182, v156
	v_pk_mul_f32 v[184:185], v[140:141], v[140:141]
	v_add_f32_e32 v156, v183, v156
	v_lshlrev_b32_e32 v142, 16, v145
	v_and_b32_e32 v143, 0xffff0000, v145
	v_add_f32_e32 v156, v184, v156
	v_pk_mul_f32 v[186:187], v[142:143], v[142:143]
	v_add_f32_e32 v156, v185, v156
	v_lshlrev_b32_e32 v144, 16, v146
	v_and_b32_e32 v145, 0xffff0000, v146
	v_add_f32_e32 v156, v186, v156
	v_pk_mul_f32 v[188:189], v[144:145], v[144:145]
	v_add_f32_e32 v156, v187, v156
	v_lshlrev_b32_e32 v146, 16, v147
	v_and_b32_e32 v147, 0xffff0000, v147
	v_add_f32_e32 v156, v188, v156
	v_pk_mul_f32 v[190:191], v[146:147], v[146:147]
	v_add_f32_e32 v156, v189, v156
	s_waitcnt vmcnt(0)
	v_lshlrev_b32_e32 v148, 16, v152
	v_and_b32_e32 v149, 0xffff0000, v152
	v_add_f32_e32 v156, v190, v156
	v_pk_mul_f32 v[192:193], v[148:149], v[148:149]
	v_add_f32_e32 v156, v191, v156
	v_lshlrev_b32_e32 v150, 16, v153
	v_and_b32_e32 v151, 0xffff0000, v153
	v_add_f32_e32 v156, v192, v156
	v_pk_mul_f32 v[194:195], v[150:151], v[150:151]
	v_add_f32_e32 v156, v193, v156
	v_lshlrev_b32_e32 v152, 16, v154
	v_and_b32_e32 v153, 0xffff0000, v154
	v_add_f32_e32 v156, v194, v156
	v_pk_mul_f32 v[196:197], v[152:153], v[152:153]
	v_add_f32_e32 v156, v195, v156
	v_lshlrev_b32_e32 v154, 16, v155
	v_and_b32_e32 v155, 0xffff0000, v155
	v_add_f32_e32 v156, v196, v156
	v_pk_mul_f32 v[198:199], v[154:155], v[154:155]
	v_add_f32_e32 v156, v197, v156
	v_add_f32_e32 v156, v198, v156
	v_add_f32_e32 v156, v199, v156
	s_waitcnt lgkmcnt(0)
	s_nop 1
	v_add_f32_dpp v156, v156, v156 quad_perm:[1,0,3,2] row_mask:0xf bank_mask:0xf
	s_waitcnt lgkmcnt(0)
	s_nop 1
	v_add_f32_dpp v156, v156, v156 quad_perm:[2,3,0,1] row_mask:0xf bank_mask:0xf
	s_waitcnt lgkmcnt(0)
	s_nop 1
	v_add_f32_dpp v156, v156, v156 row_half_mirror row_mask:0xf bank_mask:0xf
	s_waitcnt lgkmcnt(0)
	s_nop 1
	v_add_f32_dpp v156, v156, v156 row_mirror row_mask:0xf bank_mask:0xf
	s_waitcnt lgkmcnt(0)
	s_nop 1
	v_add_f32_dpp v156, v156, v156 row_bcast:15 row_mask:0xa bank_mask:0xf
	s_waitcnt lgkmcnt(0)
	s_nop 1
	v_add_f32_dpp v156, v156, v156 row_bcast:31 row_mask:0xc bank_mask:0xf
	s_nop 0
	v_readlane_b32 s99, v156, 63
	s_nop 1
	v_mov_b32_e32 v156, s99
	v_fmamk_f32 v156, v156, 0x3a000000, v162
	v_mul_f32_e32 v163, 0x4b800000, v156
	v_cmp_gt_f32_e32 vcc, s46, v156
	s_nop 1
	v_cndmask_b32_e32 v156, v156, v163, vcc
	v_rsq_f32_e32 v156, v156
	s_nop 0
	v_mul_f32_e32 v163, 0x45800000, v156
	v_cndmask_b32_e32 v156, v156, v163, vcc
	s_and_saveexec_b64 s[6:7], s[4:5]
	s_cbranch_execz .LBB0_603
	s_add_u32 s30, s80, s49
	s_addc_u32 s31, s81, s50
	global_store_dword v33, v156, s[30:31]
	s_branch .LBB0_603

; __device__ __forceinline__ float wave_sum(float v) {
; #pragma unroll
;     for (int o = 1; o < 64; o <<= 1) v += __shfl_xor(v, o);
;     return v;
; }
; __device__ __forceinline__ void phase_final(const Args& a, int lane, int wave) {
;     ...
;         for (int r = 0; r < 16; ++r) {
;             const size_t ro = (size_t)(m0 + r) * D + 8 * lane;
;             const float rstd1 = rs[m0 + r];
;             float y[4][8], z[4][8]; float ss = 0.f;
; #pragma unroll
;             for (int j = 0; j < 4; ++j) { unpack8(*(const v4u*)(Y2 + ro + 512 * j), z[j]); unpack8(*(const v4u*)(Yb + ro + 512 * j), y[j]);
; #pragma unroll
;                 for (int e = 0; e < 8; ++e) ss += z[j][e] * z[j][e]; }
;             const float rstd = rsqrtf(wave_sum(ss) * (1.0f / D) + EPS);
; #pragma unroll
;             for (int j = 0; j < 4; ++j) { f32x4 xa = *(const f32x4*)(a.in[I_X] + ro + 512 * j), xb = *(const f32x4*)(a.in[I_X] + ro + 512 * j + 4);
.LBB0_894:
	v_lshl_add_u64 v[0:1], s[80:81], 0, v[36:37]
	v_add_co_u32_e32 v2, vcc, 0xe800000, v0
	s_add_u32 s16, s80, s29
	v_lshl_add_u64 v[108:109], v[40:41], 0, s[14:15]
	v_addc_co_u32_e32 v3, vcc, 0, v1, vcc
	s_addc_u32 s17, s81, s30
	global_load_dwordx4 v[136:139], v[108:109], off
	global_load_dwordx4 v[140:143], v[108:109], off offset:16
	global_load_dword v106, v13, s[16:17]
	global_load_dwordx4 v[112:115], v[2:3], off
	global_load_dwordx4 v[116:119], v[2:3], off offset:1024
	global_load_dwordx4 v[144:147], v[2:3], off offset:2048
	global_load_dwordx4 v[148:151], v[2:3], off offset:3072
	v_add_co_u32_e32 v0, vcc, 0x16800000, v0
	v_lshl_add_u64 v[110:111], v[38:39], 0, s[14:15]
	s_nop 0
	v_addc_co_u32_e32 v1, vcc, 0, v1, vcc
	global_load_dwordx4 v[152:155], v[0:1], off
	global_load_dwordx4 v[8:11], v[0:1], off offset:1024
	global_load_dwordx4 v[4:7], v[0:1], off offset:2048
	s_nop 0
	global_load_dwordx4 v[0:3], v[0:1], off offset:3072
	s_add_u32 s14, s14, 0x2000
	s_addc_u32 s15, s15, 0
	s_add_u32 s29, s29, 4
	s_addc_u32 s30, s30, 0
	v_lshl_add_u64 v[36:37], v[36:37], 0, s[10:11]
	s_cmp_eq_u32 s14, 0x20000
	s_waitcnt vmcnt(7)
	v_lshlrev_b32_e32 v160, 16, v112
	v_and_b32_e32 v161, 0xffff0000, v112
	v_lshlrev_b32_e32 v162, 16, v113
	v_and_b32_e32 v163, 0xffff0000, v113
	v_pk_mul_f32 v[170:171], v[160:161], v[160:161]
	v_pk_mul_f32 v[172:173], v[162:163], v[162:163]
	v_add_f32_e32 v135, v170, v171
	v_lshlrev_b32_e32 v156, 16, v114
	v_and_b32_e32 v157, 0xffff0000, v114
	v_add_f32_e32 v135, v172, v135
	s_waitcnt vmcnt(6)
	v_lshlrev_b32_e32 v124, 16, v118
	v_and_b32_e32 v125, 0xffff0000, v118
	v_lshlrev_b32_e32 v128, 16, v119
	v_and_b32_e32 v129, 0xffff0000, v119
	v_lshlrev_b32_e32 v164, 16, v116
	v_and_b32_e32 v165, 0xffff0000, v116
	v_lshlrev_b32_e32 v166, 16, v117
	v_and_b32_e32 v167, 0xffff0000, v117
	s_waitcnt vmcnt(4)
	v_lshlrev_b32_e32 v116, 16, v148
	v_and_b32_e32 v117, 0xffff0000, v148
	v_lshlrev_b32_e32 v118, 16, v149
	v_and_b32_e32 v119, 0xffff0000, v149
	v_pk_mul_f32 v[148:149], v[156:157], v[156:157]
	v_add_f32_e32 v135, v173, v135
	v_lshlrev_b32_e32 v158, 16, v115
	v_and_b32_e32 v159, 0xffff0000, v115
	v_add_f32_e32 v135, v148, v135
	v_lshlrev_b32_e32 v120, 16, v146
	v_and_b32_e32 v121, 0xffff0000, v146
	v_lshlrev_b32_e32 v122, 16, v147
	v_and_b32_e32 v123, 0xffff0000, v147
	v_lshlrev_b32_e32 v112, 16, v150
	v_and_b32_e32 v113, 0xffff0000, v150
	v_lshlrev_b32_e32 v114, 16, v151
	v_and_b32_e32 v115, 0xffff0000, v151
	s_waitcnt vmcnt(3)
	v_lshlrev_b32_e32 v146, 16, v154
	v_and_b32_e32 v147, 0xffff0000, v154
	v_lshlrev_b32_e32 v150, 16, v155
	v_and_b32_e32 v151, 0xffff0000, v155
	v_pk_mul_f32 v[154:155], v[158:159], v[158:159]
	v_add_f32_e32 v135, v149, v135
	v_add_f32_e32 v135, v154, v135
	v_pk_mul_f32 v[178:179], v[164:165], v[164:165]
	v_add_f32_e32 v135, v155, v135
	v_add_f32_e32 v135, v178, v135
	v_pk_mul_f32 v[180:181], v[166:167], v[166:167]
	v_add_f32_e32 v135, v179, v135
	v_add_f32_e32 v135, v180, v135
	v_pk_mul_f32 v[174:175], v[124:125], v[124:125]
	v_add_f32_e32 v135, v181, v135
	v_add_f32_e32 v135, v174, v135
	v_pk_mul_f32 v[176:177], v[128:129], v[128:129]
	v_add_f32_e32 v135, v175, v135
	v_lshlrev_b32_e32 v126, 16, v144
	v_and_b32_e32 v127, 0xffff0000, v144
	v_add_f32_e32 v135, v176, v135
	v_pk_mul_f32 v[186:187], v[126:127], v[126:127]
	v_add_f32_e32 v135, v177, v135
	v_lshlrev_b32_e32 v144, 16, v145
	v_and_b32_e32 v145, 0xffff0000, v145
	v_add_f32_e32 v135, v186, v135
	v_pk_mul_f32 v[188:189], v[144:145], v[144:145]
	v_add_f32_e32 v135, v187, v135
	v_add_f32_e32 v135, v188, v135
	v_pk_mul_f32 v[182:183], v[120:121], v[120:121]
	v_add_f32_e32 v135, v189, v135
	v_add_f32_e32 v135, v182, v135
	v_pk_mul_f32 v[184:185], v[122:123], v[122:123]
	v_add_f32_e32 v135, v183, v135
	v_add_f32_e32 v135, v184, v135
	v_pk_mul_f32 v[194:195], v[116:117], v[116:117]
	v_add_f32_e32 v135, v185, v135
	v_add_f32_e32 v135, v194, v135
	v_pk_mul_f32 v[196:197], v[118:119], v[118:119]
	v_add_f32_e32 v135, v195, v135
	v_add_f32_e32 v135, v196, v135
	v_pk_mul_f32 v[190:191], v[112:113], v[112:113]
	v_add_f32_e32 v135, v197, v135
	v_add_f32_e32 v135, v190, v135
	v_pk_mul_f32 v[192:193], v[114:115], v[114:115]
	v_add_f32_e32 v135, v191, v135
	v_add_f32_e32 v135, v192, v135
	v_pk_mul_f32 v[146:147], v[106:107], v[146:147] op_sel_hi:[0,1]
	v_add_f32_e32 v135, v193, v135
	v_pk_fma_f32 v[140:141], v[50:51], v[146:147], v[140:141]
	v_lshlrev_b32_e32 v168, 16, v152
	v_and_b32_e32 v169, 0xffff0000, v152
	v_lshlrev_b32_e32 v152, 16, v153
	v_and_b32_e32 v153, 0xffff0000, v153
	s_waitcnt lgkmcnt(0)
	s_nop 1
	v_add_f32_dpp v135, v135, v135 quad_perm:[1,0,3,2] row_mask:0xf bank_mask:0xf
	v_pk_mul_f32 v[168:169], v[106:107], v[168:169] op_sel_hi:[0,1]
	v_pk_mul_f32 v[152:153], v[106:107], v[152:153] op_sel_hi:[0,1]
	v_pk_mul_f32 v[150:151], v[106:107], v[150:151] op_sel_hi:[0,1]
	v_pk_fma_f32 v[136:137], v[42:43], v[168:169], v[136:137]
	s_waitcnt lgkmcnt(0)
	s_nop 1
	v_add_f32_dpp v135, v135, v135 quad_perm:[2,3,0,1] row_mask:0xf bank_mask:0xf
	v_pk_fma_f32 v[138:139], v[46:47], v[152:153], v[138:139]
	v_pk_fma_f32 v[142:143], v[54:55], v[150:151], v[142:143]
	s_waitcnt lgkmcnt(0)
	s_nop 1
	v_add_f32_dpp v135, v135, v135 row_half_mirror row_mask:0xf bank_mask:0xf
	s_waitcnt lgkmcnt(0)
	s_nop 1
	v_add_f32_dpp v135, v135, v135 row_mirror row_mask:0xf bank_mask:0xf
	s_waitcnt lgkmcnt(0)
	s_nop 1
	v_add_f32_dpp v135, v135, v135 row_bcast:15 row_mask:0xa bank_mask:0xf
	s_waitcnt lgkmcnt(0)
; __device__ __forceinline__ void phase_final(const Args& a, int lane, int wave) {
;     ...
;             const float rstd = rsqrtf(wave_sum(ss) * (1.0f / D) + EPS);
; #pragma unroll
;             for (int j = 0; j < 4; ++j) { f32x4 xa = *(const f32x4*)(a.in[I_X] + ro + 512 * j), xb = *(const f32x4*)(a.in[I_X] + ro + 512 * j + 4);
; #pragma unroll
;                 for (int e = 0; e < 4; ++e) { xa[e] = (xa[e] + G1[j][e] * (y[j][e] * rstd1)) + G2[j][e] * (z[j][e] * rstd); xb[e] = (xb[e] + G1[j][e + 4] * (y[j][e + 4] * rstd1)) + G2[j][e + 4] * (z[j][e + 4] * rstd); }
;                 *(f32x4*)(a.out + ro + 512 * j) = xa; *(f32x4*)(a.out + ro + 512 * j + 4) = xb; }
;         }
;     }
	s_nop 1
	v_add_f32_dpp v135, v135, v135 row_bcast:31 row_mask:0xc bank_mask:0xf
	s_nop 0
	v_readlane_b32 s99, v135, 63
	s_nop 1
	v_mov_b32_e32 v135, s99
	v_fmamk_f32 v135, v135, 0x3a000000, v134
	v_mul_f32_e32 v146, 0x4b800000, v135
	v_cmp_gt_f32_e32 vcc, s27, v135
	s_nop 1
	v_cndmask_b32_e32 v135, v135, v146, vcc
	v_rsq_f32_e32 v135, v135
	s_nop 0
	v_mul_f32_e32 v146, 0x45800000, v135
	v_cndmask_b32_e32 v146, v135, v146, vcc
	v_pk_mul_f32 v[148:149], v[146:147], v[160:161] op_sel_hi:[0,1]
	v_pk_mul_f32 v[152:153], v[146:147], v[162:163] op_sel_hi:[0,1]
	v_pk_mul_f32 v[150:151], v[146:147], v[156:157] op_sel_hi:[0,1]
	v_pk_mul_f32 v[154:155], v[146:147], v[158:159] op_sel_hi:[0,1]
	v_pk_fma_f32 v[136:137], v[44:45], v[148:149], v[136:137]
	v_pk_fma_f32 v[138:139], v[48:49], v[152:153], v[138:139]
	v_pk_fma_f32 v[140:141], v[52:53], v[150:151], v[140:141]
	v_pk_fma_f32 v[142:143], v[56:57], v[154:155], v[142:143]
	global_store_dwordx4 v[110:111], v[136:139], off
	global_store_dwordx4 v[110:111], v[140:143], off offset:16
	global_load_dwordx4 v[136:139], v[108:109], off offset:2048
	s_nop 0
	global_load_dwordx4 v[140:143], v[108:109], off offset:2064
	s_waitcnt vmcnt(6)
	v_lshlrev_b32_e32 v154, 16, v8
	v_and_b32_e32 v155, 0xffff0000, v8
	v_lshlrev_b32_e32 v8, 16, v9
	v_and_b32_e32 v9, 0xffff0000, v9
	v_lshlrev_b32_e32 v152, 16, v10
	v_and_b32_e32 v153, 0xffff0000, v10
	v_lshlrev_b32_e32 v10, 16, v11
	v_and_b32_e32 v11, 0xffff0000, v11
	v_pk_mul_f32 v[154:155], v[106:107], v[154:155] op_sel_hi:[0,1]
	v_pk_mul_f32 v[8:9], v[106:107], v[8:9] op_sel_hi:[0,1]
	v_pk_mul_f32 v[152:153], v[106:107], v[152:153] op_sel_hi:[0,1]
	v_pk_mul_f32 v[10:11], v[106:107], v[10:11] op_sel_hi:[0,1]
	v_pk_mul_f32 v[156:157], v[146:147], v[164:165] op_sel_hi:[0,1]
	v_pk_mul_f32 v[158:159], v[146:147], v[166:167] op_sel_hi:[0,1]
	v_add_co_u32_e32 v150, vcc, s28, v108
	v_pk_mul_f32 v[124:125], v[146:147], v[124:125] op_sel_hi:[0,1]
	v_pk_mul_f32 v[128:129], v[146:147], v[128:129] op_sel_hi:[0,1]
	v_addc_co_u32_e32 v151, vcc, 0, v109, vcc
	v_lshl_add_u64 v[148:149], v[108:109], 0, s[10:11]
	v_pk_mul_f32 v[126:127], v[146:147], v[126:127] op_sel_hi:[0,1]
	v_pk_mul_f32 v[120:121], v[146:147], v[120:121] op_sel_hi:[0,1]
	v_pk_mul_f32 v[122:123], v[146:147], v[122:123] op_sel_hi:[0,1]
	v_lshl_add_u64 v[108:109], v[108:109], 0, s[12:13]
	v_pk_mul_f32 v[116:117], v[146:147], v[116:117] op_sel_hi:[0,1]
	v_pk_mul_f32 v[118:119], v[146:147], v[118:119] op_sel_hi:[0,1]
	v_pk_mul_f32 v[112:113], v[146:147], v[112:113] op_sel_hi:[0,1]
	v_pk_mul_f32 v[114:115], v[146:147], v[114:115] op_sel_hi:[0,1]
	s_waitcnt vmcnt(1)
	v_pk_fma_f32 v[136:137], v[58:59], v[154:155], v[136:137]
	v_pk_fma_f32 v[138:139], v[62:63], v[8:9], v[138:139]
	s_waitcnt vmcnt(0)
	v_pk_fma_f32 v[140:141], v[66:67], v[152:153], v[140:141]
	v_pk_fma_f32 v[142:143], v[70:71], v[10:11], v[142:143]
	v_pk_fma_f32 v[8:9], v[60:61], v[156:157], v[136:137]
	v_pk_fma_f32 v[10:11], v[64:65], v[158:159], v[138:139]
	v_pk_fma_f32 v[136:137], v[68:69], v[124:125], v[140:141]
	v_pk_fma_f32 v[138:139], v[72:73], v[128:129], v[142:143]
	global_store_dwordx4 v[110:111], v[8:11], off offset:2048
	global_store_dwordx4 v[110:111], v[136:139], off offset:2064
	global_load_dwordx4 v[8:11], v[150:151], off
	s_nop 0
	global_load_dwordx4 v[136:139], v[148:149], off offset:16
	v_lshlrev_b32_e32 v128, 16, v4
	v_and_b32_e32 v129, 0xffff0000, v4
	v_lshlrev_b32_e32 v4, 16, v5
	v_and_b32_e32 v5, 0xffff0000, v5
	v_lshlrev_b32_e32 v124, 16, v6
	v_and_b32_e32 v125, 0xffff0000, v6
	v_lshlrev_b32_e32 v6, 16, v7
	v_and_b32_e32 v7, 0xffff0000, v7
	v_pk_mul_f32 v[128:129], v[106:107], v[128:129] op_sel_hi:[0,1]
	v_pk_mul_f32 v[4:5], v[106:107], v[4:5] op_sel_hi:[0,1]
	v_add_co_u32_e32 v110, vcc, s28, v110
	v_pk_mul_f32 v[124:125], v[106:107], v[124:125] op_sel_hi:[0,1]
	v_pk_mul_f32 v[6:7], v[106:107], v[6:7] op_sel_hi:[0,1]
	v_pk_mul_f32 v[140:141], v[146:147], v[144:145] op_sel_hi:[0,1]
	v_addc_co_u32_e32 v111, vcc, 0, v111, vcc
	s_waitcnt vmcnt(1)
	v_pk_fma_f32 v[8:9], v[74:75], v[128:129], v[8:9]
	v_pk_fma_f32 v[10:11], v[78:79], v[4:5], v[10:11]
	s_waitcnt vmcnt(0)
	v_pk_fma_f32 v[124:125], v[82:83], v[124:125], v[136:137]
	v_pk_fma_f32 v[128:129], v[86:87], v[6:7], v[138:139]
	v_pk_fma_f32 v[4:5], v[76:77], v[126:127], v[8:9]
	v_pk_fma_f32 v[6:7], v[80:81], v[140:141], v[10:11]
	v_pk_fma_f32 v[8:9], v[84:85], v[120:121], v[124:125]
	v_pk_fma_f32 v[10:11], v[88:89], v[122:123], v[128:129]
	global_store_dwordx4 v[110:111], v[4:7], off
	global_store_dwordx4 v[110:111], v[8:11], off offset:16
	global_load_dwordx4 v[4:7], v[150:151], off offset:2048
	s_nop 0
	global_load_dwordx4 v[8:11], v[108:109], off offset:16
	v_lshlrev_b32_e32 v120, 16, v0
	v_and_b32_e32 v121, 0xffff0000, v0
	v_lshlrev_b32_e32 v0, 16, v1
	v_and_b32_e32 v1, 0xffff0000, v1
	v_lshlrev_b32_e32 v108, 16, v2
	v_and_b32_e32 v109, 0xffff0000, v2
	v_lshlrev_b32_e32 v2, 16, v3
	v_and_b32_e32 v3, 0xffff0000, v3
	v_pk_mul_f32 v[120:121], v[106:107], v[120:121] op_sel_hi:[0,1]
	v_pk_mul_f32 v[0:1], v[106:107], v[0:1] op_sel_hi:[0,1]
	v_pk_mul_f32 v[108:109], v[106:107], v[108:109] op_sel_hi:[0,1]
	v_pk_mul_f32 v[2:3], v[106:107], v[2:3] op_sel_hi:[0,1]
	s_waitcnt vmcnt(1)
	v_pk_fma_f32 v[4:5], v[90:91], v[120:121], v[4:5]
	v_pk_fma_f32 v[6:7], v[94:95], v[0:1], v[6:7]
	s_waitcnt vmcnt(0)
	v_pk_fma_f32 v[8:9], v[98:99], v[108:109], v[8:9]
	v_pk_fma_f32 v[10:11], v[102:103], v[2:3], v[10:11]
	v_pk_fma_f32 v[0:1], v[92:93], v[116:117], v[4:5]
	v_pk_fma_f32 v[2:3], v[96:97], v[118:119], v[6:7]
	v_pk_fma_f32 v[4:5], v[100:101], v[112:113], v[8:9]
	v_pk_fma_f32 v[6:7], v[104:105], v[114:115], v[10:11]
	global_store_dwordx4 v[110:111], v[0:3], off offset:2048
	global_store_dwordx4 v[110:111], v[4:7], off offset:2064
	s_cbranch_scc0 .LBB0_894
	s_add_i32 s20, s20, s23
	s_add_i32 s0, s0, s24
	s_cmpk_gt_i32 s20, 0x7ff
	s_cbranch_scc0 .LBB0_893
